# v36 + first two counted DMA waits of each non-first GEMM unit relaxed by the number of in-flight epilogue stores (K-loop restart no longer waits for store acks)
# baseline (speedup 1.0000x reference)
; #define PG8_STAGE(bufoff, gbase, voff) do { _Pragma("unroll") for (int _i = 0; _i < 2; ++_i) \
;         __builtin_amdgcn_global_load_lds((const unsigned*)((const char*)(gbase) + (voff)[_i]), (PG8_LAS unsigned*)(lds + (bufoff) + ldsw + _i * 8192), 16, 0, 0); } while (0)
; #define PG8_LDA(dst, b, h) do { _Pragma("unroll") for (int m = 0; m < 4; ++m) _Pragma("unroll") for (int k = 0; k < 2; ++k) dst[m][k] = *(const PG8_LAS bf16x8*)(lds + PG8_SA(b, h) + aoff + m * 2048 + k * 1024); } while (0)
; #define PG8_LDB(dst, b, h) do { _Pragma("unroll") for (int n = 0; n < 2; ++n) _Pragma("unroll") for (int k = 0; k < 2; ++k) dst[n][k] = *(const PG8_LAS bf16x8*)(lds + PG8_SB(b, h) + boff + n * 2048 + k * 1024); } while (0)
; #define PG8_WAIT_V(n) asm volatile("s_waitcnt vmcnt(" #n ")" ::: "memory")
; #define PG8_WAIT_L(n) asm volatile("s_waitcnt lgkmcnt(" #n ")" ::: "memory")
; #define PG8_BAR __builtin_amdgcn_s_barrier()
; #define PG8_SCHED __builtin_amdgcn_sched_barrier(0)
; template <class Epi, class Sched, bool ALIGN_EPI = false, bool SP2 = false>
; __device__ __forceinline__ void gemm_phase(PG8_LAS unsigned char* lds, const int tid, const Gemm g, const Sched& S, const Epi& E) {
;     ...
;             const bool last = (t == nt - 2);
;             const char* a1 = cA + (size_t)(t + 1) * kstep;
;             const char* a2 = last ? nA : cA + (size_t)(t + 2) * kstep; const char* b2 = last ? nB : cB + (size_t)(t + 2) * kstep;
;             const char* a3 = a2 + kstep; const char* b3 = b2 + kstep;
;             if (last && has_next) S.a_ready(nxt);
;             if constexpr (SP2) {
;             PG8_LDB(B0, 0, 0); PG8_LDB(B1, 0, 1); PG8_SCHED; PG8_LDA(At, 0, 0); PG8_STAGE(PG8_SA(1, 1), a1 + hstep, voffA);
;             PG8_WAIT_V(8); PG8_WAIT_L(0); PG8_BAR; PG8_MMA(0, 0, At, B0); PG8_MMA(0, 1, At, B1); PG8_BAR; PG8_SCHED;
;             PG8_LDA(At, 0, 1); PG8_STAGE(PG8_SB(0, 0), b2, voffB); PG8_STAGE(PG8_SB(0, 1), b2 + hstep, voffB); PG8_STAGE(PG8_SA(0, 0), a2, voffA);
;             PG8_WAIT_V(8); PG8_WAIT_L(0); PG8_BAR; PG8_MMA(1, 0, At, B0); PG8_MMA(1, 1, At, B1); PG8_BAR; PG8_SCHED;
;             PG8_LDB(B0, 1, 0); PG8_LDB(B1, 1, 1); PG8_SCHED; PG8_LDA(At, 1, 0); PG8_STAGE(PG8_SA(0, 1), a2 + hstep, voffA);
;             PG8_WAIT_V(8); PG8_WAIT_L(0); PG8_BAR; PG8_MMA(0, 0, At, B0); PG8_MMA(0, 1, At, B1); PG8_BAR; PG8_SCHED;
.LBB0_129:
	s_ashr_i32 s55, s54, 31
	s_lshl_b64 s[26:27], s[54:55], 19
	v_readlane_b32 s60, v251, 16
	v_readlane_b32 s61, v251, 17
	s_add_u32 s58, s60, s26
	s_addc_u32 s59, s61, s27
	s_and_b64 s[4:5], s[4:5], exec
	s_cselect_b32 s26, s59, s3
	s_cselect_b32 s27, s58, s2
	s_add_u32 s2, s2, 0x40080
	s_addc_u32 s3, s3, 0
	s_add_u32 s38, s24, 0x100
	s_addc_u32 s39, s25, 0
	s_mov_b32 s41, -2
	v_readlane_b32 s62, v251, 18
	v_readlane_b32 s63, v251, 19
	s_add_u32 s4, s2, 0xfffc0080
	s_addc_u32 s5, s3, -1
	s_cmp_eq_u32 s41, 12
	s_cselect_b32 s25, s26, s5
	s_cselect_b32 s24, s27, s4
	s_cselect_b32 s5, s57, s39
	s_cselect_b32 s4, s56, s38
	ds_read_b128 v[48:51], v243
	ds_read_b128 v[52:55], v244
	ds_read_b128 v[56:59], v243 offset:2048
	ds_read_b128 v[60:63], v244 offset:2048
	ds_read_b128 v[80:83], v243 offset:16384
	ds_read_b128 v[84:87], v244 offset:16384
	ds_read_b128 v[88:91], v243 offset:18432
	ds_read_b128 v[92:95], v244 offset:18432
	s_add_i32 m0, s17, 0xc000
	ds_read_b128 v[194:197], v204
	ds_read_b128 v[206:209], v242
	ds_read_b128 v[210:213], v204 offset:2048
	ds_read_b128 v[214:217], v242 offset:2048
	ds_read_b128 v[218:221], v204 offset:4096
	ds_read_b128 v[230:233], v242 offset:4096
	ds_read_b128 v[234:237], v204 offset:6144
	ds_read_b128 v[238:241], v242 offset:6144
	global_load_lds_dwordx4 v190, s[2:3]
	s_add_i32 m0, s17, 0xe000
	s_nop 0
	global_load_lds_dwordx4 v192, s[2:3]
	s_cmp_eq_u32 s68, 1
	s_cbranch_scc1 .Lstrict_g1_0
	s_waitcnt vmcnt(16)
	s_branch .Ljoinw_g1_0
.Lstrict_g1_0:
	s_waitcnt vmcnt(8)
.Ljoinw_g1_0:
	s_waitcnt lgkmcnt(0)
	s_barrier
	s_setprio 1
	s_waitcnt lgkmcnt(0)
	v_mfma_f32_16x16x32_bf16 v[156:159], v[48:51], v[194:197], 0
	v_mfma_f32_16x16x32_bf16 v[152:155], v[56:59], v[194:197], 0
	v_mfma_f32_16x16x32_bf16 v[140:143], v[48:51], v[210:213], 0
	v_mfma_f32_16x16x32_bf16 v[136:139], v[56:59], v[210:213], 0
	v_mfma_f32_16x16x32_bf16 v[124:127], v[48:51], v[218:221], 0
	v_mfma_f32_16x16x32_bf16 v[120:123], v[56:59], v[218:221], 0
	v_mfma_f32_16x16x32_bf16 v[108:111], v[48:51], v[234:237], 0
	v_mfma_f32_16x16x32_bf16 v[104:107], v[56:59], v[234:237], 0
	v_mfma_f32_16x16x32_bf16 v[156:159], v[52:55], v[206:209], v[156:159]
	v_mfma_f32_16x16x32_bf16 v[152:155], v[60:63], v[206:209], v[152:155]
	v_mfma_f32_16x16x32_bf16 v[140:143], v[52:55], v[214:217], v[140:143]
	v_mfma_f32_16x16x32_bf16 v[136:139], v[60:63], v[214:217], v[136:139]
	v_mfma_f32_16x16x32_bf16 v[124:127], v[52:55], v[230:233], v[124:127]
	v_mfma_f32_16x16x32_bf16 v[120:123], v[60:63], v[230:233], v[120:123]
	v_mfma_f32_16x16x32_bf16 v[108:111], v[52:55], v[238:241], v[108:111]
	v_mfma_f32_16x16x32_bf16 v[104:107], v[60:63], v[238:241], v[104:107]
	s_setprio 0
	s_setprio 1
	v_mfma_f32_16x16x32_bf16 v[148:151], v[80:83], v[194:197], 0
	v_mfma_f32_16x16x32_bf16 v[144:147], v[88:91], v[194:197], 0
	v_mfma_f32_16x16x32_bf16 v[132:135], v[80:83], v[210:213], 0
	v_mfma_f32_16x16x32_bf16 v[128:131], v[88:91], v[210:213], 0
	v_mfma_f32_16x16x32_bf16 v[116:119], v[80:83], v[218:221], 0
	v_mfma_f32_16x16x32_bf16 v[112:115], v[88:91], v[218:221], 0
	v_mfma_f32_16x16x32_bf16 v[100:103], v[80:83], v[234:237], 0
	v_mfma_f32_16x16x32_bf16 v[96:99], v[88:91], v[234:237], 0
	v_mfma_f32_16x16x32_bf16 v[148:151], v[84:87], v[206:209], v[148:151]
	v_mfma_f32_16x16x32_bf16 v[144:147], v[92:95], v[206:209], v[144:147]
	v_mfma_f32_16x16x32_bf16 v[132:135], v[84:87], v[214:217], v[132:135]
	v_mfma_f32_16x16x32_bf16 v[128:131], v[92:95], v[214:217], v[128:131]
	v_mfma_f32_16x16x32_bf16 v[116:119], v[84:87], v[230:233], v[116:119]
	v_mfma_f32_16x16x32_bf16 v[112:115], v[92:95], v[230:233], v[112:115]
	v_mfma_f32_16x16x32_bf16 v[100:103], v[84:87], v[238:241], v[100:103]
	v_mfma_f32_16x16x32_bf16 v[96:99], v[92:95], v[238:241], v[96:99]
	s_setprio 0
	s_barrier
	s_add_i32 m0, s16, 0x10000
	ds_read_b128 v[194:197], v204 offset:16384
	ds_read_b128 v[206:209], v242 offset:16384
	ds_read_b128 v[210:213], v204 offset:18432
	ds_read_b128 v[214:217], v242 offset:18432
	ds_read_b128 v[218:221], v204 offset:20480
	ds_read_b128 v[230:233], v242 offset:20480
	ds_read_b128 v[234:237], v204 offset:22528
	ds_read_b128 v[238:241], v242 offset:22528
	global_load_lds_dwordx4 v164, s[4:5]
	s_add_i32 m0, s16, 0x12000
	s_add_u32 s60, s4, 0x40000
	s_addc_u32 s61, s5, 0
	global_load_lds_dwordx4 v160, s[4:5]
	s_add_i32 m0, s16, 0x14000
	s_nop 0
	global_load_lds_dwordx4 v164, s[60:61]
	s_add_i32 m0, s16, 0x16000
	s_nop 0
	global_load_lds_dwordx4 v160, s[60:61]
	s_mov_b32 m0, s17
	s_nop 0
	global_load_lds_dwordx4 v166, s[24:25]
	s_mov_b32 m0, s18
	s_nop 0
	global_load_lds_dwordx4 v162, s[24:25]
	s_cmp_eq_u32 s68, 1
	s_cbranch_scc1 .Lstrict_g1_1
	s_waitcnt vmcnt(16)
	s_branch .Ljoinw_g1_1

; #define PG8_STAGE(bufoff, gbase, voff) do { _Pragma("unroll") for (int _i = 0; _i < 2; ++_i) \
;         __builtin_amdgcn_global_load_lds((const unsigned*)((const char*)(gbase) + (voff)[_i]), (PG8_LAS unsigned*)(lds + (bufoff) + ldsw + _i * 8192), 16, 0, 0); } while (0)
; #define PG8_LDA(dst, b, h) do { _Pragma("unroll") for (int m = 0; m < 4; ++m) _Pragma("unroll") for (int k = 0; k < 2; ++k) dst[m][k] = *(const PG8_LAS bf16x8*)(lds + PG8_SA(b, h) + aoff + m * 2048 + k * 1024); } while (0)
; #define PG8_LDB(dst, b, h) do { _Pragma("unroll") for (int n = 0; n < 2; ++n) _Pragma("unroll") for (int k = 0; k < 2; ++k) dst[n][k] = *(const PG8_LAS bf16x8*)(lds + PG8_SB(b, h) + boff + n * 2048 + k * 1024); } while (0)
; #define PG8_MMA(ai, bj, At, Bt) do { __builtin_amdgcn_s_setprio(1); _Pragma("unroll") for (int m = 0; m < 4; ++m) _Pragma("unroll") for (int n = 0; n < 2; ++n) _Pragma("unroll") for (int k = 0; k < 2; ++k) \
;         acc[ai][bj][m][n] = __builtin_amdgcn_mfma_f32_16x16x32_bf16(Bt[n][k], At[m][k], acc[ai][bj][m][n], 0, 0, 0); __builtin_amdgcn_s_setprio(0); } while (0)
; #define PG8_WAIT_V(n) asm volatile("s_waitcnt vmcnt(" #n ")" ::: "memory")
; #define PG8_WAIT_L(n) asm volatile("s_waitcnt lgkmcnt(" #n ")" ::: "memory")
; #define PG8_BAR __builtin_amdgcn_s_barrier()
; #define PG8_SCHED __builtin_amdgcn_sched_barrier(0)
; template <class Epi, class Sched, bool ALIGN_EPI = false, bool SP2 = false>
; __device__ __forceinline__ void gemm_phase(PG8_LAS unsigned char* lds, const int tid, const Gemm g, const Sched& S, const Epi& E) {
;     ...
;             PG8_WAIT_V(8); PG8_WAIT_L(0); PG8_BAR; PG8_MMA(1, 0, At, B0); PG8_MMA(1, 1, At, B1); PG8_BAR; PG8_SCHED;
;             PG8_LDB(B0, 1, 0); PG8_LDB(B1, 1, 1); PG8_SCHED; PG8_LDA(At, 1, 0); PG8_STAGE(PG8_SA(0, 1), a2 + hstep, voffA);
;             PG8_WAIT_V(8); PG8_WAIT_L(0); PG8_BAR; PG8_MMA(0, 0, At, B0); PG8_MMA(0, 1, At, B1); PG8_BAR; PG8_SCHED;
.Ljoinw_g1_1:
	s_waitcnt lgkmcnt(0)
	s_barrier
	s_setprio 1
	s_waitcnt lgkmcnt(0)
	v_mfma_f32_16x16x32_bf16 v[76:79], v[48:51], v[194:197], 0
	v_mfma_f32_16x16x32_bf16 v[72:75], v[56:59], v[194:197], 0
	v_mfma_f32_16x16x32_bf16 v[44:47], v[48:51], v[210:213], 0
	v_mfma_f32_16x16x32_bf16 v[40:43], v[56:59], v[210:213], 0
	v_mfma_f32_16x16x32_bf16 v[28:31], v[48:51], v[218:221], 0
	v_mfma_f32_16x16x32_bf16 v[24:27], v[56:59], v[218:221], 0
	v_mfma_f32_16x16x32_bf16 v[12:15], v[48:51], v[234:237], 0
	v_mfma_f32_16x16x32_bf16 v[8:11], v[56:59], v[234:237], 0
	v_mfma_f32_16x16x32_bf16 v[76:79], v[52:55], v[206:209], v[76:79]
	v_mfma_f32_16x16x32_bf16 v[72:75], v[60:63], v[206:209], v[72:75]
	v_mfma_f32_16x16x32_bf16 v[44:47], v[52:55], v[214:217], v[44:47]
	v_mfma_f32_16x16x32_bf16 v[40:43], v[60:63], v[214:217], v[40:43]
	v_mfma_f32_16x16x32_bf16 v[28:31], v[52:55], v[230:233], v[28:31]
	v_mfma_f32_16x16x32_bf16 v[24:27], v[60:63], v[230:233], v[24:27]
	v_mfma_f32_16x16x32_bf16 v[12:15], v[52:55], v[238:241], v[12:15]
	v_mfma_f32_16x16x32_bf16 v[8:11], v[60:63], v[238:241], v[8:11]
	s_setprio 0
	s_setprio 1
	v_mfma_f32_16x16x32_bf16 v[36:39], v[80:83], v[210:213], 0
	v_mfma_f32_16x16x32_bf16 v[32:35], v[88:91], v[210:213], 0
	v_mfma_f32_16x16x32_bf16 v[20:23], v[80:83], v[218:221], 0
	v_mfma_f32_16x16x32_bf16 v[16:19], v[88:91], v[218:221], 0
	v_mfma_f32_16x16x32_bf16 v[4:7], v[80:83], v[234:237], 0
	v_mfma_f32_16x16x32_bf16 v[0:3], v[88:91], v[234:237], 0
	v_mfma_f32_16x16x32_bf16 v[48:51], v[80:83], v[194:197], 0
	v_mfma_f32_16x16x32_bf16 v[52:55], v[88:91], v[194:197], 0
	v_mfma_f32_16x16x32_bf16 v[36:39], v[84:87], v[214:217], v[36:39]
	v_mfma_f32_16x16x32_bf16 v[32:35], v[92:95], v[214:217], v[32:35]
	v_mfma_f32_16x16x32_bf16 v[20:23], v[84:87], v[230:233], v[20:23]
	v_mfma_f32_16x16x32_bf16 v[16:19], v[92:95], v[230:233], v[16:19]
	v_mfma_f32_16x16x32_bf16 v[4:7], v[84:87], v[238:241], v[4:7]
	v_mfma_f32_16x16x32_bf16 v[0:3], v[92:95], v[238:241], v[0:3]
	v_mfma_f32_16x16x32_bf16 v[48:51], v[84:87], v[206:209], v[48:51]
	v_mfma_f32_16x16x32_bf16 v[52:55], v[92:95], v[206:209], v[52:55]
	s_setprio 0
	s_barrier
	ds_read_b128 v[56:59], v243 offset:32768
	ds_read_b128 v[60:63], v244 offset:32768
	ds_read_b128 v[64:67], v243 offset:34816
	ds_read_b128 v[68:71], v244 offset:34816
	ds_read_b128 v[80:83], v243 offset:49152
	ds_read_b128 v[84:87], v244 offset:49152
	ds_read_b128 v[88:91], v243 offset:51200
	ds_read_b128 v[92:95], v244 offset:51200
	s_add_u32 s24, s24, 0x40000
	s_addc_u32 s25, s25, 0
	s_mov_b32 m0, s19
	ds_read_b128 v[194:197], v204 offset:32768
	ds_read_b128 v[206:209], v242 offset:32768
	ds_read_b128 v[210:213], v204 offset:34816
	ds_read_b128 v[214:217], v242 offset:34816
	ds_read_b128 v[218:221], v204 offset:36864
	ds_read_b128 v[230:233], v242 offset:36864
	ds_read_b128 v[234:237], v204 offset:38912
	ds_read_b128 v[238:241], v242 offset:38912
	global_load_lds_dwordx4 v166, s[24:25]
	s_mov_b32 m0, s20
	s_nop 0
	global_load_lds_dwordx4 v162, s[24:25]
	s_waitcnt vmcnt(8)
	s_waitcnt lgkmcnt(0)
	s_barrier
	s_setprio 1
	s_waitcnt lgkmcnt(0)
	v_mfma_f32_16x16x32_bf16 v[156:159], v[56:59], v[194:197], v[156:159]
	v_mfma_f32_16x16x32_bf16 v[152:155], v[64:67], v[194:197], v[152:155]
	v_mfma_f32_16x16x32_bf16 v[140:143], v[56:59], v[210:213], v[140:143]
	v_mfma_f32_16x16x32_bf16 v[136:139], v[64:67], v[210:213], v[136:139]
	v_mfma_f32_16x16x32_bf16 v[124:127], v[56:59], v[218:221], v[124:127]
	v_mfma_f32_16x16x32_bf16 v[120:123], v[64:67], v[218:221], v[120:123]
	v_mfma_f32_16x16x32_bf16 v[108:111], v[56:59], v[234:237], v[108:111]
	v_mfma_f32_16x16x32_bf16 v[104:107], v[64:67], v[234:237], v[104:107]
	v_mfma_f32_16x16x32_bf16 v[156:159], v[60:63], v[206:209], v[156:159]
	v_mfma_f32_16x16x32_bf16 v[152:155], v[68:71], v[206:209], v[152:155]
	v_mfma_f32_16x16x32_bf16 v[140:143], v[60:63], v[214:217], v[140:143]
	v_mfma_f32_16x16x32_bf16 v[136:139], v[68:71], v[214:217], v[136:139]
	v_mfma_f32_16x16x32_bf16 v[124:127], v[60:63], v[230:233], v[124:127]
	v_mfma_f32_16x16x32_bf16 v[120:123], v[68:71], v[230:233], v[120:123]
	v_mfma_f32_16x16x32_bf16 v[108:111], v[60:63], v[238:241], v[108:111]
	v_mfma_f32_16x16x32_bf16 v[104:107], v[68:71], v[238:241], v[104:107]
	s_setprio 0
	s_setprio 1
	v_mfma_f32_16x16x32_bf16 v[148:151], v[80:83], v[194:197], v[148:151]
	v_mfma_f32_16x16x32_bf16 v[144:147], v[88:91], v[194:197], v[144:147]
	v_mfma_f32_16x16x32_bf16 v[132:135], v[80:83], v[210:213], v[132:135]
	v_mfma_f32_16x16x32_bf16 v[128:131], v[88:91], v[210:213], v[128:131]
	v_mfma_f32_16x16x32_bf16 v[116:119], v[80:83], v[218:221], v[116:119]
	v_mfma_f32_16x16x32_bf16 v[112:115], v[88:91], v[218:221], v[112:115]
	v_mfma_f32_16x16x32_bf16 v[100:103], v[80:83], v[234:237], v[100:103]
	v_mfma_f32_16x16x32_bf16 v[96:99], v[88:91], v[234:237], v[96:99]
	v_mfma_f32_16x16x32_bf16 v[148:151], v[84:87], v[206:209], v[148:151]
	v_mfma_f32_16x16x32_bf16 v[144:147], v[92:95], v[206:209], v[144:147]
	v_mfma_f32_16x16x32_bf16 v[132:135], v[84:87], v[214:217], v[132:135]
	v_mfma_f32_16x16x32_bf16 v[128:131], v[92:95], v[214:217], v[128:131]
	v_mfma_f32_16x16x32_bf16 v[116:119], v[84:87], v[230:233], v[116:119]
	v_mfma_f32_16x16x32_bf16 v[112:115], v[92:95], v[230:233], v[112:115]
	v_mfma_f32_16x16x32_bf16 v[100:103], v[84:87], v[238:241], v[100:103]
	v_mfma_f32_16x16x32_bf16 v[96:99], v[92:95], v[238:241], v[96:99]
	s_setprio 0
	s_barrier
; #define PG8_STAGE(bufoff, gbase, voff) do { _Pragma("unroll") for (int _i = 0; _i < 2; ++_i) \
;         __builtin_amdgcn_global_load_lds((const unsigned*)((const char*)(gbase) + (voff)[_i]), (PG8_LAS unsigned*)(lds + (bufoff) + ldsw + _i * 8192), 16, 0, 0); } while (0)
; #define PG8_LDA(dst, b, h) do { _Pragma("unroll") for (int m = 0; m < 4; ++m) _Pragma("unroll") for (int k = 0; k < 2; ++k) dst[m][k] = *(const PG8_LAS bf16x8*)(lds + PG8_SA(b, h) + aoff + m * 2048 + k * 1024); } while (0)
; #define PG8_MMA(ai, bj, At, Bt) do { __builtin_amdgcn_s_setprio(1); _Pragma("unroll") for (int m = 0; m < 4; ++m) _Pragma("unroll") for (int n = 0; n < 2; ++n) _Pragma("unroll") for (int k = 0; k < 2; ++k) \
;         acc[ai][bj][m][n] = __builtin_amdgcn_mfma_f32_16x16x32_bf16(Bt[n][k], At[m][k], acc[ai][bj][m][n], 0, 0, 0); __builtin_amdgcn_s_setprio(0); } while (0)
; #define PG8_WAIT_V(n) asm volatile("s_waitcnt vmcnt(" #n ")" ::: "memory")
; #define PG8_WAIT_L(n) asm volatile("s_waitcnt lgkmcnt(" #n ")" ::: "memory")
; #define PG8_BAR __builtin_amdgcn_s_barrier()
; #define PG8_SCHED __builtin_amdgcn_sched_barrier(0)
; template <class Epi, class Sched, bool ALIGN_EPI = false, bool SP2 = false>
; __device__ __forceinline__ void gemm_phase(PG8_LAS unsigned char* lds, const int tid, const Gemm g, const Sched& S, const Epi& E) {
;     ...
;         for (int t = 0; t < nt; t += 2) {
;             const bool last = (t == nt - 2);
;             const char* a1 = cA + (size_t)(t + 1) * kstep;
;             const char* a2 = last ? nA : cA + (size_t)(t + 2) * kstep; const char* b2 = last ? nB : cB + (size_t)(t + 2) * kstep;
;     ...
;             PG8_LDA(At, 1, 1); PG8_STAGE(PG8_SB(1, 0), b3, voffB); PG8_STAGE(PG8_SB(1, 1), b3 + hstep, voffB); PG8_STAGE(PG8_SA(1, 0), a3, voffA);
;             PG8_WAIT_V(8); PG8_WAIT_L(0); PG8_BAR; PG8_MMA(1, 0, At, B0); PG8_MMA(1, 1, At, B1); PG8_BAR; PG8_SCHED;
	s_add_u32 s94, s4, 0x80
	s_addc_u32 s95, s5, 0
	s_add_i32 m0, s16, 0x18000
	ds_read_b128 v[194:197], v204 offset:49152
	ds_read_b128 v[206:209], v242 offset:49152
	ds_read_b128 v[210:213], v204 offset:51200
	ds_read_b128 v[214:217], v242 offset:51200
	ds_read_b128 v[218:221], v204 offset:53248
	ds_read_b128 v[230:233], v242 offset:53248
	ds_read_b128 v[234:237], v204 offset:55296
	ds_read_b128 v[238:241], v242 offset:55296
	global_load_lds_dwordx4 v164, s[94:95]
	s_add_i32 m0, s16, 0x1a000
	s_add_u32 s4, s4, 0x40080
	s_addc_u32 s5, s5, 0
	global_load_lds_dwordx4 v160, s[94:95]
	s_add_i32 m0, s16, 0x1c000
	s_add_u32 s92, s24, 0xfffc0080
	s_addc_u32 s93, s25, -1
	global_load_lds_dwordx4 v164, s[4:5]
	s_add_i32 m0, s16, 0x1e000
	s_nop 0
	global_load_lds_dwordx4 v160, s[4:5]
	s_mov_b32 m0, s66
	s_nop 0
	global_load_lds_dwordx4 v166, s[92:93]
	s_mov_b32 m0, s67
	s_nop 0
	global_load_lds_dwordx4 v162, s[92:93]
	s_waitcnt vmcnt(8)
	s_waitcnt lgkmcnt(0)
	s_barrier
	s_setprio 1
	s_waitcnt lgkmcnt(0)
	v_mfma_f32_16x16x32_bf16 v[76:79], v[56:59], v[194:197], v[76:79]
	v_mfma_f32_16x16x32_bf16 v[72:75], v[64:67], v[194:197], v[72:75]
	v_mfma_f32_16x16x32_bf16 v[44:47], v[56:59], v[210:213], v[44:47]
	v_mfma_f32_16x16x32_bf16 v[40:43], v[64:67], v[210:213], v[40:43]
	v_mfma_f32_16x16x32_bf16 v[28:31], v[56:59], v[218:221], v[28:31]
	v_mfma_f32_16x16x32_bf16 v[24:27], v[64:67], v[218:221], v[24:27]
	v_mfma_f32_16x16x32_bf16 v[12:15], v[56:59], v[234:237], v[12:15]
	v_mfma_f32_16x16x32_bf16 v[8:11], v[64:67], v[234:237], v[8:11]
	v_mfma_f32_16x16x32_bf16 v[76:79], v[60:63], v[206:209], v[76:79]
	v_mfma_f32_16x16x32_bf16 v[72:75], v[68:71], v[206:209], v[72:75]
	v_mfma_f32_16x16x32_bf16 v[44:47], v[60:63], v[214:217], v[44:47]
	v_mfma_f32_16x16x32_bf16 v[40:43], v[68:71], v[214:217], v[40:43]
	v_mfma_f32_16x16x32_bf16 v[28:31], v[60:63], v[230:233], v[28:31]
	v_mfma_f32_16x16x32_bf16 v[24:27], v[68:71], v[230:233], v[24:27]
	v_mfma_f32_16x16x32_bf16 v[12:15], v[60:63], v[238:241], v[12:15]
	v_mfma_f32_16x16x32_bf16 v[8:11], v[68:71], v[238:241], v[8:11]
	s_setprio 0
	s_setprio 1
	v_mfma_f32_16x16x32_bf16 v[48:51], v[80:83], v[194:197], v[48:51]
	v_mfma_f32_16x16x32_bf16 v[68:71], v[84:87], v[206:209], v[48:51]
	v_mfma_f32_16x16x32_bf16 v[48:51], v[88:91], v[194:197], v[52:55]
	v_mfma_f32_16x16x32_bf16 v[36:39], v[80:83], v[210:213], v[36:39]
	v_mfma_f32_16x16x32_bf16 v[32:35], v[88:91], v[210:213], v[32:35]
	v_mfma_f32_16x16x32_bf16 v[20:23], v[80:83], v[218:221], v[20:23]
	v_mfma_f32_16x16x32_bf16 v[16:19], v[88:91], v[218:221], v[16:19]
	v_mfma_f32_16x16x32_bf16 v[4:7], v[80:83], v[234:237], v[4:7]
	v_mfma_f32_16x16x32_bf16 v[0:3], v[88:91], v[234:237], v[0:3]
	v_mfma_f32_16x16x32_bf16 v[64:67], v[92:95], v[206:209], v[48:51]
	v_mfma_f32_16x16x32_bf16 v[36:39], v[84:87], v[214:217], v[36:39]
	v_mfma_f32_16x16x32_bf16 v[32:35], v[92:95], v[214:217], v[32:35]
	v_mfma_f32_16x16x32_bf16 v[20:23], v[84:87], v[230:233], v[20:23]
	v_mfma_f32_16x16x32_bf16 v[16:19], v[92:95], v[230:233], v[16:19]
	v_mfma_f32_16x16x32_bf16 v[4:7], v[84:87], v[238:241], v[4:7]
	v_mfma_f32_16x16x32_bf16 v[0:3], v[92:95], v[238:241], v[0:3]
	s_setprio 0
	s_barrier
	s_add_i32 s41, s41, 2
	s_add_u32 s2, s2, 0x100
	s_addc_u32 s3, s3, 0
	s_add_u32 s38, s38, 0x100
	s_addc_u32 s39, s39, 0
	s_cmp_gt_u32 s41, 13
	s_cbranch_scc0 .LBB0_130
	s_branch .Lpeel_exit_g1

; #define PG8_STAGE(bufoff, gbase, voff) do { _Pragma("unroll") for (int _i = 0; _i < 2; ++_i) \
;         __builtin_amdgcn_global_load_lds((const unsigned*)((const char*)(gbase) + (voff)[_i]), (PG8_LAS unsigned*)(lds + (bufoff) + ldsw + _i * 8192), 16, 0, 0); } while (0)
; #define PG8_LDA(dst, b, h) do { _Pragma("unroll") for (int m = 0; m < 4; ++m) _Pragma("unroll") for (int k = 0; k < 2; ++k) dst[m][k] = *(const PG8_LAS bf16x8*)(lds + PG8_SA(b, h) + aoff + m * 2048 + k * 1024); } while (0)
; #define PG8_LDB(dst, b, h) do { _Pragma("unroll") for (int n = 0; n < 2; ++n) _Pragma("unroll") for (int k = 0; k < 2; ++k) dst[n][k] = *(const PG8_LAS bf16x8*)(lds + PG8_SB(b, h) + boff + n * 2048 + k * 1024); } while (0)
; #define PG8_MMA(ai, bj, At, Bt) do { __builtin_amdgcn_s_setprio(1); _Pragma("unroll") for (int m = 0; m < 4; ++m) _Pragma("unroll") for (int n = 0; n < 2; ++n) _Pragma("unroll") for (int k = 0; k < 2; ++k) \
;         acc[ai][bj][m][n] = __builtin_amdgcn_mfma_f32_16x16x32_bf16(Bt[n][k], At[m][k], acc[ai][bj][m][n], 0, 0, 0); __builtin_amdgcn_s_setprio(0); } while (0)
; #define PG8_WAIT_V(n) asm volatile("s_waitcnt vmcnt(" #n ")" ::: "memory")
; #define PG8_WAIT_L(n) asm volatile("s_waitcnt lgkmcnt(" #n ")" ::: "memory")
; #define PG8_BAR __builtin_amdgcn_s_barrier()
;     __device__ __forceinline__ void operator()(const f32x4 (&acc)[2][2][4][2], const Unit& u, int wr, int wc, int fr, int fq) const {
;     ...
;         const float* swp = sw + (size_t)((u.pm * BM) >> 13) * (2 * 2816) + u.pn * BM + wc * 32 + 8 * fq;
;         f32x4 sv[2][2];
; #pragma unroll
;         for (int bj = 0; bj < 2; ++bj)
; #pragma unroll
;             for (int n = 0; n < 2; ++n) sv[bj][n] = *(const f32x4*)(swp + bj * HALF + 4 * n);
;         float rsv[2][4];
; #pragma unroll
;         for (int ai = 0; ai < 2; ++ai)
; #pragma unroll
;             for (int m = 0; m < 4; ++m) rsv[ai][m] = rss[row0 + ai * HALF + m * 16];
; template <class Epi, class Sched, bool ALIGN_EPI = false, bool SP2 = false>
; __device__ __forceinline__ void gemm_phase(PG8_LAS unsigned char* lds, const int tid, const Gemm g, const Sched& S, const Epi& E) {
;     ...
;             PG8_LDB(B0, 0, 0); PG8_LDB(B1, 0, 1); PG8_SCHED; PG8_LDA(At, 0, 0); PG8_STAGE(PG8_SA(1, 1), a1 + hstep, voffA);
;             PG8_WAIT_V(8); PG8_WAIT_L(0); PG8_BAR; PG8_MMA(0, 0, At, B0); PG8_MMA(0, 1, At, B1); PG8_BAR; PG8_SCHED;
.LBB0_425:
	s_ashr_i32 s41, s40, 31
	s_lshl_b64 s[44:45], s[40:41], 19
	v_readlane_b32 s48, v251, 16
	v_readlane_b32 s49, v251, 17
	s_add_u32 s44, s48, s44
	s_addc_u32 s45, s49, s45
	s_and_b64 s[4:5], s[4:5], exec
	s_cselect_b32 s39, s45, s27
	s_cselect_b32 s41, s44, s26
	s_add_u32 s4, s26, 0x40080
	s_addc_u32 s5, s27, 0
	s_add_u32 s46, s24, 0x100
	s_addc_u32 s47, s25, 0
	s_mov_b32 s48, -2
	v_readlane_b32 s50, v251, 18
	v_readlane_b32 s51, v251, 19
	s_and_b32 s90, s20, 1
	s_lshl_b32 s90, s90, 11
	s_add_i32 s90, s90, 0x20000
	s_ashr_i32 s92, s23, 5
	s_mul_hi_i32 s93, s92, 0x5800
	s_mul_i32 s92, s92, 0x5800
	s_add_u32 s92, s8, s92
	s_addc_u32 s93, s9, s93
	s_lshl_b32 s94, s22, 10
	s_add_u32 s92, s92, s94
	s_addc_u32 s93, s93, 0
	s_mov_b32 m0, s90
	s_nop 0
	global_load_lds_dwordx4 v234, s[92:93]
	s_lshl_b32 s94, s23, 10
	s_add_u32 s92, s6, s94
	s_addc_u32 s93, s7, 0
	s_add_i32 m0, s90, 0x400
	s_nop 0
	global_load_lds_dwordx4 v234, s[92:93]
	s_add_u32 s24, s4, 0xfffc0080
	s_addc_u32 s25, s5, -1
	s_cmp_eq_u32 s48, 12
	s_cselect_b32 s27, s39, s25
	s_cselect_b32 s26, s41, s24
	s_cselect_b32 s25, s43, s47
	s_cselect_b32 s24, s42, s46
	ds_read_b128 v[64:67], v244
	ds_read_b128 v[68:71], v245
	ds_read_b128 v[72:75], v244 offset:2048
	ds_read_b128 v[76:79], v245 offset:2048
	ds_read_b128 v[154:157], v244 offset:16384
	ds_read_b128 v[164:167], v245 offset:16384
	ds_read_b128 v[186:189], v244 offset:18432
	ds_read_b128 v[190:193], v245 offset:18432
	s_add_i32 m0, s14, 0xc000
	ds_read_b128 v[194:197], v161
	ds_read_b128 v[198:201], v249
	ds_read_b128 v[202:205], v161 offset:2048
	ds_read_b128 v[206:209], v249 offset:2048
	ds_read_b128 v[210:213], v161 offset:4096
	ds_read_b128 v[214:217], v249 offset:4096
	ds_read_b128 v[218:221], v161 offset:6144
	ds_read_b128 v[230:233], v249 offset:6144
	global_load_lds_dwordx4 v150, s[4:5]
	s_add_i32 m0, s14, 0xe000
	s_nop 0
	global_load_lds_dwordx4 v152, s[4:5]
	s_cmp_eq_u32 s20, 1
	s_cbranch_scc1 .Lstrict_g3_0
	s_waitcnt vmcnt(18)
	s_branch .Ljoinw_g3_0

; #define PG8_STAGE(bufoff, gbase, voff) do { _Pragma("unroll") for (int _i = 0; _i < 2; ++_i) \
;         __builtin_amdgcn_global_load_lds((const unsigned*)((const char*)(gbase) + (voff)[_i]), (PG8_LAS unsigned*)(lds + (bufoff) + ldsw + _i * 8192), 16, 0, 0); } while (0)
; #define PG8_LDA(dst, b, h) do { _Pragma("unroll") for (int m = 0; m < 4; ++m) _Pragma("unroll") for (int k = 0; k < 2; ++k) dst[m][k] = *(const PG8_LAS bf16x8*)(lds + PG8_SA(b, h) + aoff + m * 2048 + k * 1024); } while (0)
; #define PG8_MMA(ai, bj, At, Bt) do { __builtin_amdgcn_s_setprio(1); _Pragma("unroll") for (int m = 0; m < 4; ++m) _Pragma("unroll") for (int n = 0; n < 2; ++n) _Pragma("unroll") for (int k = 0; k < 2; ++k) \
;         acc[ai][bj][m][n] = __builtin_amdgcn_mfma_f32_16x16x32_bf16(Bt[n][k], At[m][k], acc[ai][bj][m][n], 0, 0, 0); __builtin_amdgcn_s_setprio(0); } while (0)
; #define PG8_WAIT_V(n) asm volatile("s_waitcnt vmcnt(" #n ")" ::: "memory")
; #define PG8_WAIT_L(n) asm volatile("s_waitcnt lgkmcnt(" #n ")" ::: "memory")
; #define PG8_BAR __builtin_amdgcn_s_barrier()
; #define PG8_SCHED __builtin_amdgcn_sched_barrier(0)
; template <class Epi, class Sched, bool ALIGN_EPI = false, bool SP2 = false>
; __device__ __forceinline__ void gemm_phase(PG8_LAS unsigned char* lds, const int tid, const Gemm g, const Sched& S, const Epi& E) {
;     ...
;             PG8_WAIT_V(8); PG8_WAIT_L(0); PG8_BAR; PG8_MMA(0, 0, At, B0); PG8_MMA(0, 1, At, B1); PG8_BAR; PG8_SCHED;
;             PG8_LDA(At, 0, 1); PG8_STAGE(PG8_SB(0, 0), b2, voffB); PG8_STAGE(PG8_SB(0, 1), b2 + hstep, voffB); PG8_STAGE(PG8_SA(0, 0), a2, voffA);
;             PG8_WAIT_V(8); PG8_WAIT_L(0); PG8_BAR; PG8_MMA(1, 0, At, B0); PG8_MMA(1, 1, At, B1); PG8_BAR; PG8_SCHED;
.Ljoinw_g3_0:
	s_waitcnt lgkmcnt(0)
	s_barrier
	s_setprio 1
	s_waitcnt lgkmcnt(0)
	v_mfma_f32_16x16x32_bf16 v[140:143], v[64:67], v[194:197], 0
	v_mfma_f32_16x16x32_bf16 v[136:139], v[72:75], v[194:197], 0
	v_mfma_f32_16x16x32_bf16 v[124:127], v[64:67], v[202:205], 0
	v_mfma_f32_16x16x32_bf16 v[120:123], v[72:75], v[202:205], 0
	v_mfma_f32_16x16x32_bf16 v[108:111], v[64:67], v[210:213], 0
	v_mfma_f32_16x16x32_bf16 v[104:107], v[72:75], v[210:213], 0
	v_mfma_f32_16x16x32_bf16 v[92:95], v[64:67], v[218:221], 0
	v_mfma_f32_16x16x32_bf16 v[88:91], v[72:75], v[218:221], 0
	v_mfma_f32_16x16x32_bf16 v[140:143], v[68:71], v[198:201], v[140:143]
	v_mfma_f32_16x16x32_bf16 v[136:139], v[76:79], v[198:201], v[136:139]
	v_mfma_f32_16x16x32_bf16 v[124:127], v[68:71], v[206:209], v[124:127]
	v_mfma_f32_16x16x32_bf16 v[120:123], v[76:79], v[206:209], v[120:123]
	v_mfma_f32_16x16x32_bf16 v[108:111], v[68:71], v[214:217], v[108:111]
	v_mfma_f32_16x16x32_bf16 v[104:107], v[76:79], v[214:217], v[104:107]
	v_mfma_f32_16x16x32_bf16 v[92:95], v[68:71], v[230:233], v[92:95]
	v_mfma_f32_16x16x32_bf16 v[88:91], v[76:79], v[230:233], v[88:91]
	s_setprio 0
	s_setprio 1
	v_mfma_f32_16x16x32_bf16 v[132:135], v[154:157], v[194:197], 0
	v_mfma_f32_16x16x32_bf16 v[128:131], v[186:189], v[194:197], 0
	v_mfma_f32_16x16x32_bf16 v[116:119], v[154:157], v[202:205], 0
	v_mfma_f32_16x16x32_bf16 v[112:115], v[186:189], v[202:205], 0
	v_mfma_f32_16x16x32_bf16 v[100:103], v[154:157], v[210:213], 0
	v_mfma_f32_16x16x32_bf16 v[96:99], v[186:189], v[210:213], 0
	v_mfma_f32_16x16x32_bf16 v[84:87], v[154:157], v[218:221], 0
	v_mfma_f32_16x16x32_bf16 v[80:83], v[186:189], v[218:221], 0
	v_mfma_f32_16x16x32_bf16 v[132:135], v[164:167], v[198:201], v[132:135]
	v_mfma_f32_16x16x32_bf16 v[128:131], v[190:193], v[198:201], v[128:131]
	v_mfma_f32_16x16x32_bf16 v[116:119], v[164:167], v[206:209], v[116:119]
	v_mfma_f32_16x16x32_bf16 v[112:115], v[190:193], v[206:209], v[112:115]
	v_mfma_f32_16x16x32_bf16 v[100:103], v[164:167], v[214:217], v[100:103]
	v_mfma_f32_16x16x32_bf16 v[96:99], v[190:193], v[214:217], v[96:99]
	v_mfma_f32_16x16x32_bf16 v[84:87], v[164:167], v[230:233], v[84:87]
	v_mfma_f32_16x16x32_bf16 v[80:83], v[190:193], v[230:233], v[80:83]
	s_setprio 0
	s_barrier
	s_add_i32 m0, s12, 0x10000
	ds_read_b128 v[194:197], v161 offset:16384
	ds_read_b128 v[198:201], v249 offset:16384
	ds_read_b128 v[202:205], v161 offset:18432
	ds_read_b128 v[206:209], v249 offset:18432
	ds_read_b128 v[210:213], v161 offset:20480
	ds_read_b128 v[214:217], v249 offset:20480
	ds_read_b128 v[218:221], v161 offset:22528
	ds_read_b128 v[230:233], v249 offset:22528
	global_load_lds_dwordx4 v168, s[24:25]
	s_add_i32 m0, s12, 0x12000
	s_add_u32 s50, s24, 0x40000
	s_addc_u32 s51, s25, 0
	global_load_lds_dwordx4 v144, s[24:25]
	s_add_i32 m0, s12, 0x14000
	s_nop 0
	global_load_lds_dwordx4 v168, s[50:51]
	s_add_i32 m0, s12, 0x16000
	s_nop 0
	global_load_lds_dwordx4 v144, s[50:51]
	s_mov_b32 m0, s14
	s_nop 0
	global_load_lds_dwordx4 v148, s[26:27]
	s_mov_b32 m0, s15
	s_nop 0
	global_load_lds_dwordx4 v146, s[26:27]
	s_cmp_eq_u32 s20, 1
	s_cbranch_scc1 .Lstrict_g3_1
	s_waitcnt vmcnt(18)
	s_branch .Ljoinw_g3_1

; #define PG8_STAGE(bufoff, gbase, voff) do { _Pragma("unroll") for (int _i = 0; _i < 2; ++_i) \
;         __builtin_amdgcn_global_load_lds((const unsigned*)((const char*)(gbase) + (voff)[_i]), (PG8_LAS unsigned*)(lds + (bufoff) + ldsw + _i * 8192), 16, 0, 0); } while (0)
; #define PG8_LDA(dst, b, h) do { _Pragma("unroll") for (int m = 0; m < 4; ++m) _Pragma("unroll") for (int k = 0; k < 2; ++k) dst[m][k] = *(const PG8_LAS bf16x8*)(lds + PG8_SA(b, h) + aoff + m * 2048 + k * 1024); } while (0)
; #define PG8_LDB(dst, b, h) do { _Pragma("unroll") for (int n = 0; n < 2; ++n) _Pragma("unroll") for (int k = 0; k < 2; ++k) dst[n][k] = *(const PG8_LAS bf16x8*)(lds + PG8_SB(b, h) + boff + n * 2048 + k * 1024); } while (0)
; #define PG8_MMA(ai, bj, At, Bt) do { __builtin_amdgcn_s_setprio(1); _Pragma("unroll") for (int m = 0; m < 4; ++m) _Pragma("unroll") for (int n = 0; n < 2; ++n) _Pragma("unroll") for (int k = 0; k < 2; ++k) \
;         acc[ai][bj][m][n] = __builtin_amdgcn_mfma_f32_16x16x32_bf16(Bt[n][k], At[m][k], acc[ai][bj][m][n], 0, 0, 0); __builtin_amdgcn_s_setprio(0); } while (0)
; #define PG8_WAIT_V(n) asm volatile("s_waitcnt vmcnt(" #n ")" ::: "memory")
; #define PG8_WAIT_L(n) asm volatile("s_waitcnt lgkmcnt(" #n ")" ::: "memory")
; #define PG8_BAR __builtin_amdgcn_s_barrier()
; #define PG8_SCHED __builtin_amdgcn_sched_barrier(0)
; template <class Epi, class Sched, bool ALIGN_EPI = false, bool SP2 = false>
; __device__ __forceinline__ void gemm_phase(PG8_LAS unsigned char* lds, const int tid, const Gemm g, const Sched& S, const Epi& E) {
;     ...
;             PG8_WAIT_V(8); PG8_WAIT_L(0); PG8_BAR; PG8_MMA(1, 0, At, B0); PG8_MMA(1, 1, At, B1); PG8_BAR; PG8_SCHED;
;             PG8_LDB(B0, 1, 0); PG8_LDB(B1, 1, 1); PG8_SCHED; PG8_LDA(At, 1, 0); PG8_STAGE(PG8_SA(0, 1), a2 + hstep, voffA);
;             PG8_WAIT_V(8); PG8_WAIT_L(0); PG8_BAR; PG8_MMA(0, 0, At, B0); PG8_MMA(0, 1, At, B1); PG8_BAR; PG8_SCHED;
.Ljoinw_g3_1:
	s_waitcnt lgkmcnt(0)
	s_barrier
	s_setprio 1
	s_waitcnt lgkmcnt(0)
	v_mfma_f32_16x16x32_bf16 v[60:63], v[64:67], v[194:197], 0
	v_mfma_f32_16x16x32_bf16 v[56:59], v[72:75], v[194:197], 0
	v_mfma_f32_16x16x32_bf16 v[44:47], v[64:67], v[202:205], 0
	v_mfma_f32_16x16x32_bf16 v[40:43], v[72:75], v[202:205], 0
	v_mfma_f32_16x16x32_bf16 v[28:31], v[64:67], v[210:213], 0
	v_mfma_f32_16x16x32_bf16 v[24:27], v[72:75], v[210:213], 0
	v_mfma_f32_16x16x32_bf16 v[12:15], v[64:67], v[218:221], 0
	v_mfma_f32_16x16x32_bf16 v[8:11], v[72:75], v[218:221], 0
	v_mfma_f32_16x16x32_bf16 v[60:63], v[68:71], v[198:201], v[60:63]
	v_mfma_f32_16x16x32_bf16 v[56:59], v[76:79], v[198:201], v[56:59]
	v_mfma_f32_16x16x32_bf16 v[44:47], v[68:71], v[206:209], v[44:47]
	v_mfma_f32_16x16x32_bf16 v[40:43], v[76:79], v[206:209], v[40:43]
	v_mfma_f32_16x16x32_bf16 v[28:31], v[68:71], v[214:217], v[28:31]
	v_mfma_f32_16x16x32_bf16 v[24:27], v[76:79], v[214:217], v[24:27]
	v_mfma_f32_16x16x32_bf16 v[12:15], v[68:71], v[230:233], v[12:15]
	v_mfma_f32_16x16x32_bf16 v[8:11], v[76:79], v[230:233], v[8:11]
	s_setprio 0
	s_setprio 1
	v_mfma_f32_16x16x32_bf16 v[52:55], v[154:157], v[194:197], 0
	v_mfma_f32_16x16x32_bf16 v[48:51], v[186:189], v[194:197], 0
	v_mfma_f32_16x16x32_bf16 v[36:39], v[154:157], v[202:205], 0
	v_mfma_f32_16x16x32_bf16 v[32:35], v[186:189], v[202:205], 0
	v_mfma_f32_16x16x32_bf16 v[20:23], v[154:157], v[210:213], 0
	v_mfma_f32_16x16x32_bf16 v[16:19], v[186:189], v[210:213], 0
	v_mfma_f32_16x16x32_bf16 v[4:7], v[154:157], v[218:221], 0
	v_mfma_f32_16x16x32_bf16 v[0:3], v[186:189], v[218:221], 0
	v_mfma_f32_16x16x32_bf16 v[52:55], v[164:167], v[198:201], v[52:55]
	v_mfma_f32_16x16x32_bf16 v[48:51], v[190:193], v[198:201], v[48:51]
	v_mfma_f32_16x16x32_bf16 v[36:39], v[164:167], v[206:209], v[36:39]
	v_mfma_f32_16x16x32_bf16 v[32:35], v[190:193], v[206:209], v[32:35]
	v_mfma_f32_16x16x32_bf16 v[20:23], v[164:167], v[214:217], v[20:23]
	v_mfma_f32_16x16x32_bf16 v[16:19], v[190:193], v[214:217], v[16:19]
	v_mfma_f32_16x16x32_bf16 v[4:7], v[164:167], v[230:233], v[4:7]
	v_mfma_f32_16x16x32_bf16 v[0:3], v[190:193], v[230:233], v[0:3]
	s_setprio 0
	s_barrier
	ds_read_b128 v[64:67], v244 offset:32768
	ds_read_b128 v[68:71], v245 offset:32768
	ds_read_b128 v[72:75], v244 offset:34816
	ds_read_b128 v[76:79], v245 offset:34816
	ds_read_b128 v[154:157], v244 offset:49152
	ds_read_b128 v[164:167], v245 offset:49152
	ds_read_b128 v[186:189], v244 offset:51200
	ds_read_b128 v[190:193], v245 offset:51200
	s_add_u32 s26, s26, 0x40000
	s_addc_u32 s27, s27, 0
	s_mov_b32 m0, s16
	ds_read_b128 v[194:197], v161 offset:32768
	ds_read_b128 v[198:201], v249 offset:32768
	ds_read_b128 v[202:205], v161 offset:34816
	ds_read_b128 v[206:209], v249 offset:34816
	ds_read_b128 v[210:213], v161 offset:36864
	ds_read_b128 v[214:217], v249 offset:36864
	ds_read_b128 v[218:221], v161 offset:38912
	ds_read_b128 v[230:233], v249 offset:38912
	global_load_lds_dwordx4 v148, s[26:27]
	s_mov_b32 m0, s17
	s_nop 0
	global_load_lds_dwordx4 v146, s[26:27]
	s_waitcnt vmcnt(8)
	s_waitcnt lgkmcnt(0)
	s_barrier
	s_setprio 1
	s_waitcnt lgkmcnt(0)
	v_mfma_f32_16x16x32_bf16 v[140:143], v[64:67], v[194:197], v[140:143]
	v_mfma_f32_16x16x32_bf16 v[136:139], v[72:75], v[194:197], v[136:139]
	v_mfma_f32_16x16x32_bf16 v[124:127], v[64:67], v[202:205], v[124:127]
	v_mfma_f32_16x16x32_bf16 v[120:123], v[72:75], v[202:205], v[120:123]
	v_mfma_f32_16x16x32_bf16 v[108:111], v[64:67], v[210:213], v[108:111]
	v_mfma_f32_16x16x32_bf16 v[104:107], v[72:75], v[210:213], v[104:107]
	v_mfma_f32_16x16x32_bf16 v[92:95], v[64:67], v[218:221], v[92:95]
	v_mfma_f32_16x16x32_bf16 v[88:91], v[72:75], v[218:221], v[88:91]
	v_mfma_f32_16x16x32_bf16 v[140:143], v[68:71], v[198:201], v[140:143]
	v_mfma_f32_16x16x32_bf16 v[136:139], v[76:79], v[198:201], v[136:139]
	v_mfma_f32_16x16x32_bf16 v[124:127], v[68:71], v[206:209], v[124:127]
	v_mfma_f32_16x16x32_bf16 v[120:123], v[76:79], v[206:209], v[120:123]
	v_mfma_f32_16x16x32_bf16 v[108:111], v[68:71], v[214:217], v[108:111]
	v_mfma_f32_16x16x32_bf16 v[104:107], v[76:79], v[214:217], v[104:107]
	v_mfma_f32_16x16x32_bf16 v[92:95], v[68:71], v[230:233], v[92:95]
	v_mfma_f32_16x16x32_bf16 v[88:91], v[76:79], v[230:233], v[88:91]
	s_setprio 0
	s_setprio 1
	v_mfma_f32_16x16x32_bf16 v[132:135], v[154:157], v[194:197], v[132:135]
	v_mfma_f32_16x16x32_bf16 v[128:131], v[186:189], v[194:197], v[128:131]
	v_mfma_f32_16x16x32_bf16 v[116:119], v[154:157], v[202:205], v[116:119]
	v_mfma_f32_16x16x32_bf16 v[112:115], v[186:189], v[202:205], v[112:115]
	v_mfma_f32_16x16x32_bf16 v[100:103], v[154:157], v[210:213], v[100:103]
	v_mfma_f32_16x16x32_bf16 v[96:99], v[186:189], v[210:213], v[96:99]
	v_mfma_f32_16x16x32_bf16 v[84:87], v[154:157], v[218:221], v[84:87]
	v_mfma_f32_16x16x32_bf16 v[80:83], v[186:189], v[218:221], v[80:83]
	v_mfma_f32_16x16x32_bf16 v[132:135], v[164:167], v[198:201], v[132:135]
	v_mfma_f32_16x16x32_bf16 v[128:131], v[190:193], v[198:201], v[128:131]
	v_mfma_f32_16x16x32_bf16 v[116:119], v[164:167], v[206:209], v[116:119]
	v_mfma_f32_16x16x32_bf16 v[112:115], v[190:193], v[206:209], v[112:115]
	v_mfma_f32_16x16x32_bf16 v[100:103], v[164:167], v[214:217], v[100:103]
	v_mfma_f32_16x16x32_bf16 v[96:99], v[190:193], v[214:217], v[96:99]
	v_mfma_f32_16x16x32_bf16 v[84:87], v[164:167], v[230:233], v[84:87]
	v_mfma_f32_16x16x32_bf16 v[80:83], v[190:193], v[230:233], v[80:83]
	s_setprio 0
	s_barrier
; #define PG8_STAGE(bufoff, gbase, voff) do { _Pragma("unroll") for (int _i = 0; _i < 2; ++_i) \
;         __builtin_amdgcn_global_load_lds((const unsigned*)((const char*)(gbase) + (voff)[_i]), (PG8_LAS unsigned*)(lds + (bufoff) + ldsw + _i * 8192), 16, 0, 0); } while (0)
; #define PG8_LDA(dst, b, h) do { _Pragma("unroll") for (int m = 0; m < 4; ++m) _Pragma("unroll") for (int k = 0; k < 2; ++k) dst[m][k] = *(const PG8_LAS bf16x8*)(lds + PG8_SA(b, h) + aoff + m * 2048 + k * 1024); } while (0)
; #define PG8_MMA(ai, bj, At, Bt) do { __builtin_amdgcn_s_setprio(1); _Pragma("unroll") for (int m = 0; m < 4; ++m) _Pragma("unroll") for (int n = 0; n < 2; ++n) _Pragma("unroll") for (int k = 0; k < 2; ++k) \
;         acc[ai][bj][m][n] = __builtin_amdgcn_mfma_f32_16x16x32_bf16(Bt[n][k], At[m][k], acc[ai][bj][m][n], 0, 0, 0); __builtin_amdgcn_s_setprio(0); } while (0)
; #define PG8_WAIT_V(n) asm volatile("s_waitcnt vmcnt(" #n ")" ::: "memory")
; #define PG8_WAIT_L(n) asm volatile("s_waitcnt lgkmcnt(" #n ")" ::: "memory")
; #define PG8_BAR __builtin_amdgcn_s_barrier()
; #define PG8_SCHED __builtin_amdgcn_sched_barrier(0)
; template <class Epi, class Sched, bool ALIGN_EPI = false, bool SP2 = false>
; __device__ __forceinline__ void gemm_phase(PG8_LAS unsigned char* lds, const int tid, const Gemm g, const Sched& S, const Epi& E) {
;     ...
;             PG8_LDA(At, 1, 1); PG8_STAGE(PG8_SB(1, 0), b3, voffB); PG8_STAGE(PG8_SB(1, 1), b3 + hstep, voffB); PG8_STAGE(PG8_SA(1, 0), a3, voffA);
;             PG8_WAIT_V(8); PG8_WAIT_L(0); PG8_BAR; PG8_MMA(1, 0, At, B0); PG8_MMA(1, 1, At, B1); PG8_BAR; PG8_SCHED;
	s_add_u32 s94, s24, 0x80
	s_addc_u32 s95, s25, 0
	s_add_i32 m0, s12, 0x18000
	ds_read_b128 v[194:197], v161 offset:49152
	ds_read_b128 v[198:201], v249 offset:49152
	ds_read_b128 v[202:205], v161 offset:51200
	ds_read_b128 v[206:209], v249 offset:51200
	ds_read_b128 v[210:213], v161 offset:53248
	ds_read_b128 v[214:217], v249 offset:53248
	ds_read_b128 v[218:221], v161 offset:55296
	ds_read_b128 v[230:233], v249 offset:55296
	global_load_lds_dwordx4 v168, s[94:95]
	s_add_i32 m0, s12, 0x1a000
	s_add_u32 s24, s24, 0x40080
	s_addc_u32 s25, s25, 0
	global_load_lds_dwordx4 v144, s[94:95]
	s_add_i32 m0, s12, 0x1c000
	s_add_u32 s92, s26, 0xfffc0080
	s_addc_u32 s93, s27, -1
	global_load_lds_dwordx4 v168, s[24:25]
	s_add_i32 m0, s12, 0x1e000
	s_nop 0
	global_load_lds_dwordx4 v144, s[24:25]
	s_mov_b32 m0, s18
	s_nop 0
	global_load_lds_dwordx4 v148, s[92:93]
	s_mov_b32 m0, s19
	s_nop 0
	global_load_lds_dwordx4 v146, s[92:93]
	s_waitcnt vmcnt(8)
	s_waitcnt lgkmcnt(0)
	s_barrier
	s_setprio 1
	s_waitcnt lgkmcnt(0)
	v_mfma_f32_16x16x32_bf16 v[60:63], v[64:67], v[194:197], v[60:63]
	v_mfma_f32_16x16x32_bf16 v[56:59], v[72:75], v[194:197], v[56:59]
	v_mfma_f32_16x16x32_bf16 v[44:47], v[64:67], v[202:205], v[44:47]
	v_mfma_f32_16x16x32_bf16 v[40:43], v[72:75], v[202:205], v[40:43]
	v_mfma_f32_16x16x32_bf16 v[28:31], v[64:67], v[210:213], v[28:31]
	v_mfma_f32_16x16x32_bf16 v[24:27], v[72:75], v[210:213], v[24:27]
	v_mfma_f32_16x16x32_bf16 v[12:15], v[64:67], v[218:221], v[12:15]
	v_mfma_f32_16x16x32_bf16 v[8:11], v[72:75], v[218:221], v[8:11]
	v_mfma_f32_16x16x32_bf16 v[60:63], v[68:71], v[198:201], v[60:63]
	v_mfma_f32_16x16x32_bf16 v[56:59], v[76:79], v[198:201], v[56:59]
	v_mfma_f32_16x16x32_bf16 v[44:47], v[68:71], v[206:209], v[44:47]
	v_mfma_f32_16x16x32_bf16 v[40:43], v[76:79], v[206:209], v[40:43]
	v_mfma_f32_16x16x32_bf16 v[28:31], v[68:71], v[214:217], v[28:31]
	v_mfma_f32_16x16x32_bf16 v[24:27], v[76:79], v[214:217], v[24:27]
	v_mfma_f32_16x16x32_bf16 v[12:15], v[68:71], v[230:233], v[12:15]
	v_mfma_f32_16x16x32_bf16 v[8:11], v[76:79], v[230:233], v[8:11]
	s_setprio 0
	s_setprio 1
	v_mfma_f32_16x16x32_bf16 v[52:55], v[154:157], v[194:197], v[52:55]
	v_mfma_f32_16x16x32_bf16 v[48:51], v[186:189], v[194:197], v[48:51]
	v_mfma_f32_16x16x32_bf16 v[36:39], v[154:157], v[202:205], v[36:39]
	v_mfma_f32_16x16x32_bf16 v[32:35], v[186:189], v[202:205], v[32:35]
	v_mfma_f32_16x16x32_bf16 v[20:23], v[154:157], v[210:213], v[20:23]
	v_mfma_f32_16x16x32_bf16 v[16:19], v[186:189], v[210:213], v[16:19]
	v_mfma_f32_16x16x32_bf16 v[4:7], v[154:157], v[218:221], v[4:7]
	v_mfma_f32_16x16x32_bf16 v[0:3], v[186:189], v[218:221], v[0:3]
	v_mfma_f32_16x16x32_bf16 v[52:55], v[164:167], v[198:201], v[52:55]
	v_mfma_f32_16x16x32_bf16 v[48:51], v[190:193], v[198:201], v[48:51]
	v_mfma_f32_16x16x32_bf16 v[36:39], v[164:167], v[206:209], v[36:39]
	v_mfma_f32_16x16x32_bf16 v[32:35], v[190:193], v[206:209], v[32:35]
	v_mfma_f32_16x16x32_bf16 v[20:23], v[164:167], v[214:217], v[20:23]
	v_mfma_f32_16x16x32_bf16 v[16:19], v[190:193], v[214:217], v[16:19]
	v_mfma_f32_16x16x32_bf16 v[4:7], v[164:167], v[230:233], v[4:7]
	v_mfma_f32_16x16x32_bf16 v[0:3], v[190:193], v[230:233], v[0:3]
	s_setprio 0
	s_barrier
	s_add_i32 s48, s48, 2
	s_add_u32 s4, s4, 0x100
	s_addc_u32 s5, s5, 0
	s_add_u32 s46, s46, 0x100
	s_addc_u32 s47, s47, 0
	s_cmp_gt_u32 s48, 13
	s_cbranch_scc0 .LBB0_426
	s_branch .Lpeel_exit_g3
